# grid barrier: non-leader workgroups poll the cross-XCD generation word directly instead of the per-XCD generation (one release hop fewer)
# speedup vs baseline: 1.0007x; 1.0007x over previous
.LBB0_227:
	s_or_b64 exec, exec, s[2:3]
	v_cvt_f32_u32_e32 v4, v2
	s_waitcnt vmcnt(0)
	v_readfirstlane_b32 s0, v3
	v_sub_u32_e32 v3, 0, v2
	v_rcp_iflag_f32_e32 v4, v4
	v_add_u32_e32 v5, s0, v1
	v_mul_f32_e32 v4, 0x4f7ffffe, v4
	v_cvt_u32_f32_e32 v4, v4
	v_mul_lo_u32 v1, v3, v4
	v_mul_hi_u32 v1, v4, v1
	v_add_u32_e32 v1, v4, v1
	v_mul_hi_u32 v1, v5, v1
	v_mul_lo_u32 v3, v1, v2
	v_sub_u32_e32 v3, v5, v3
	v_add_u32_e32 v4, 1, v1
	v_cmp_ge_u32_e32 vcc, v3, v2
	s_nop 1
	v_cndmask_b32_e32 v1, v1, v4, vcc
	v_sub_u32_e32 v4, v3, v2
	v_cndmask_b32_e32 v3, v3, v4, vcc
	v_add_u32_e32 v4, 1, v1
	v_cmp_ge_u32_e32 vcc, v3, v2
	v_add_u32_e32 v3, 1, v5
	s_nop 0
	v_cndmask_b32_e32 v1, v1, v4, vcc
	v_mul_lo_u32 v4, v2, v1
	v_add_u32_e32 v2, v4, v2
	v_cmp_ne_u32_e32 vcc, v3, v2
	s_and_saveexec_b64 s[0:1], vcc
	s_xor_b64 s[0:1], exec, s[0:1]
	s_cbranch_execz .LBB0_241
	s_add_i32 s2, s22, 0x900
	s_mov_b32 s3, 0
	s_lshl_b64 s[2:3], s[2:3], 2
	s_add_u32 s8, s6, 0x3500
	s_addc_u32 s9, s7, 0
	s_waitcnt lgkmcnt(0)
	v_mov_b32_e32 v0, 0
	global_load_dword v2, v0, s[8:9] sc1
	s_waitcnt vmcnt(0)
	v_cmp_eq_u32_e32 vcc, v2, v1
	s_and_saveexec_b64 s[2:3], vcc
	s_cbranch_execz .LBB0_240
	s_mov_b32 s20, 1
	s_mov_b64 s[10:11], 0
	s_branch .LBB0_231

.LBB0_500:
	s_or_b64 exec, exec, s[2:3]
	v_cvt_f32_u32_e32 v5, v3
	s_waitcnt vmcnt(0)
	v_readfirstlane_b32 s0, v4
	v_sub_u32_e32 v4, 0, v3
	v_rcp_iflag_f32_e32 v5, v5
	v_add_u32_e32 v6, s0, v1
	v_mul_f32_e32 v5, 0x4f7ffffe, v5
	v_cvt_u32_f32_e32 v5, v5
	v_mul_lo_u32 v1, v4, v5
	v_mul_hi_u32 v1, v5, v1
	v_add_u32_e32 v1, v5, v1
	v_mul_hi_u32 v1, v6, v1
	v_mul_lo_u32 v4, v1, v3
	v_sub_u32_e32 v4, v6, v4
	v_add_u32_e32 v5, 1, v1
	v_cmp_ge_u32_e32 vcc, v4, v3
	s_nop 1
	v_cndmask_b32_e32 v1, v1, v5, vcc
	v_sub_u32_e32 v5, v4, v3
	v_cndmask_b32_e32 v4, v4, v5, vcc
	v_add_u32_e32 v5, 1, v1
	v_cmp_ge_u32_e32 vcc, v4, v3
	v_add_u32_e32 v4, 1, v6
	s_nop 0
	v_cndmask_b32_e32 v1, v1, v5, vcc
	v_mul_lo_u32 v5, v3, v1
	v_add_u32_e32 v3, v5, v3
	v_cmp_ne_u32_e32 vcc, v4, v3
	s_and_saveexec_b64 s[0:1], vcc
	s_xor_b64 s[0:1], exec, s[0:1]
	s_cbranch_execz .LBB0_514
	s_add_i32 s54, s22, 0x900
	s_lshl_b64 s[2:3], s[54:55], 2
	s_add_u32 s8, s6, 0x3500
	s_addc_u32 s9, s7, 0
	s_waitcnt lgkmcnt(0)
	global_load_dword v0, v2, s[8:9] sc1
	s_waitcnt vmcnt(0)
	v_cmp_eq_u32_e32 vcc, v0, v1
	s_and_saveexec_b64 s[2:3], vcc
	s_cbranch_execz .LBB0_513
	s_mov_b32 s20, 1
	s_mov_b64 s[10:11], 0
	s_branch .LBB0_504
